# v_combo2 + PEER top-k extraction: last 8 rounds peeled with shrinking list shifts (fewer VALU ops, same values)
# speedup vs baseline: 1.0056x; 1.0056x over previous
.LBB0_1347:
	v_max_u32_dpp v55, v30, v30 row_ror:1 row_mask:0xf bank_mask:0xf bound_ctrl:1
	v_max_u32_dpp v54, v22, v22 row_ror:1 row_mask:0xf bank_mask:0xf bound_ctrl:1
	v_max_u32_dpp v56, v38, v38 row_ror:1 row_mask:0xf bank_mask:0xf bound_ctrl:1
	v_max_u32_dpp v55, v55, v55 row_ror:2 row_mask:0xf bank_mask:0xf bound_ctrl:1
	v_max_u32_dpp v57, v46, v46 row_ror:1 row_mask:0xf bank_mask:0xf bound_ctrl:1
	v_max_u32_dpp v54, v54, v54 row_ror:2 row_mask:0xf bank_mask:0xf bound_ctrl:1
	v_max_u32_dpp v56, v56, v56 row_ror:2 row_mask:0xf bank_mask:0xf bound_ctrl:1
	v_max_u32_dpp v55, v55, v55 row_ror:4 row_mask:0xf bank_mask:0xf bound_ctrl:1
	v_max_u32_dpp v57, v57, v57 row_ror:2 row_mask:0xf bank_mask:0xf bound_ctrl:1
	v_max_u32_dpp v54, v54, v54 row_ror:4 row_mask:0xf bank_mask:0xf bound_ctrl:1
	v_max_u32_dpp v56, v56, v56 row_ror:4 row_mask:0xf bank_mask:0xf bound_ctrl:1
	v_max_u32_dpp v55, v55, v55 row_ror:8 row_mask:0xf bank_mask:0xf bound_ctrl:1
	v_max_u32_dpp v57, v57, v57 row_ror:4 row_mask:0xf bank_mask:0xf bound_ctrl:1
	v_max_u32_dpp v54, v54, v54 row_ror:8 row_mask:0xf bank_mask:0xf bound_ctrl:1
	v_max_u32_dpp v56, v56, v56 row_ror:8 row_mask:0xf bank_mask:0xf bound_ctrl:1
	v_cmp_eq_u32_e64 s[0:1], v30, v55
	v_max_u32_dpp v57, v57, v57 row_ror:8 row_mask:0xf bank_mask:0xf bound_ctrl:1
	v_cmp_eq_u32_e32 vcc, v22, v54
	v_cndmask_b32_e64 v30, v30, v32, s[0:1]
	v_cndmask_b32_e64 v32, v32, v33, s[0:1]
	v_cndmask_b32_e64 v33, v33, v34, s[0:1]
	v_cndmask_b32_e64 v34, v34, v35, s[0:1]
	v_cndmask_b32_e64 v35, v35, v36, s[0:1]
	v_cndmask_b32_e64 v36, v36, v37, s[0:1]
	v_cndmask_b32_e64 v37, v37, v31, s[0:1]
	v_cndmask_b32_e64 v31, v31, 0, s[0:1]
	v_cmp_eq_u32_e64 s[0:1], v38, v56
	v_cndmask_b32_e32 v22, v22, v24, vcc
	v_cndmask_b32_e32 v24, v24, v25, vcc
	v_cndmask_b32_e32 v25, v25, v26, vcc
	v_cndmask_b32_e32 v26, v26, v27, vcc
	v_cndmask_b32_e32 v27, v27, v28, vcc
	v_cndmask_b32_e32 v28, v28, v29, vcc
	v_cndmask_b32_e32 v29, v29, v23, vcc
	v_cndmask_b32_e64 v23, v23, 0, vcc
	v_cmp_eq_u32_e32 vcc, s40, v171
	v_cndmask_b32_e64 v38, v38, v40, s[0:1]
	v_cndmask_b32_e64 v40, v40, v41, s[0:1]
	v_cndmask_b32_e64 v41, v41, v42, s[0:1]
	v_cndmask_b32_e64 v42, v42, v43, s[0:1]
	v_cndmask_b32_e64 v43, v43, v44, s[0:1]
	v_cndmask_b32_e64 v44, v44, v45, s[0:1]
	v_cndmask_b32_e64 v45, v45, v39, s[0:1]
	v_cndmask_b32_e64 v39, v39, 0, s[0:1]
	v_cmp_eq_u32_e64 s[0:1], v46, v57
	s_add_i32 s40, s40, 1
	v_cndmask_b32_e32 v18, v18, v54, vcc
	v_cndmask_b32_e32 v19, v19, v55, vcc
	v_cndmask_b32_e32 v20, v20, v56, vcc
	v_cndmask_b32_e64 v46, v46, v48, s[0:1]
	v_cndmask_b32_e64 v48, v48, v49, s[0:1]
	v_cndmask_b32_e64 v49, v49, v50, s[0:1]
	v_cndmask_b32_e64 v50, v50, v51, s[0:1]
	v_cndmask_b32_e64 v51, v51, v52, s[0:1]
	v_cndmask_b32_e64 v52, v52, v53, s[0:1]
	v_cndmask_b32_e64 v53, v53, v47, s[0:1]
	v_cndmask_b32_e64 v47, v47, 0, s[0:1]
	s_cmp_lg_u32 s40, 8
	v_cndmask_b32_e32 v21, v21, v57, vcc
	s_cbranch_scc1 .LBB0_1347
	v_max_u32_dpp v55, v30, v30 row_ror:1 row_mask:0xf bank_mask:0xf bound_ctrl:1
	v_max_u32_dpp v54, v22, v22 row_ror:1 row_mask:0xf bank_mask:0xf bound_ctrl:1
	v_max_u32_dpp v56, v38, v38 row_ror:1 row_mask:0xf bank_mask:0xf bound_ctrl:1
	v_max_u32_dpp v55, v55, v55 row_ror:2 row_mask:0xf bank_mask:0xf bound_ctrl:1
	v_max_u32_dpp v57, v46, v46 row_ror:1 row_mask:0xf bank_mask:0xf bound_ctrl:1
	v_max_u32_dpp v54, v54, v54 row_ror:2 row_mask:0xf bank_mask:0xf bound_ctrl:1
	v_max_u32_dpp v56, v56, v56 row_ror:2 row_mask:0xf bank_mask:0xf bound_ctrl:1
	v_max_u32_dpp v55, v55, v55 row_ror:4 row_mask:0xf bank_mask:0xf bound_ctrl:1
	v_max_u32_dpp v57, v57, v57 row_ror:2 row_mask:0xf bank_mask:0xf bound_ctrl:1
	v_max_u32_dpp v54, v54, v54 row_ror:4 row_mask:0xf bank_mask:0xf bound_ctrl:1
	v_max_u32_dpp v56, v56, v56 row_ror:4 row_mask:0xf bank_mask:0xf bound_ctrl:1
	v_max_u32_dpp v55, v55, v55 row_ror:8 row_mask:0xf bank_mask:0xf bound_ctrl:1
	v_max_u32_dpp v57, v57, v57 row_ror:4 row_mask:0xf bank_mask:0xf bound_ctrl:1
	v_max_u32_dpp v54, v54, v54 row_ror:8 row_mask:0xf bank_mask:0xf bound_ctrl:1
	v_max_u32_dpp v56, v56, v56 row_ror:8 row_mask:0xf bank_mask:0xf bound_ctrl:1
	v_cmp_eq_u32_e64 s[0:1], v30, v55
	v_max_u32_dpp v57, v57, v57 row_ror:8 row_mask:0xf bank_mask:0xf bound_ctrl:1
	v_cmp_eq_u32_e32 vcc, v22, v54
	v_cndmask_b32_e64 v30, v30, v32, s[0:1]
	v_cndmask_b32_e64 v32, v32, v33, s[0:1]
	v_cndmask_b32_e64 v33, v33, v34, s[0:1]
	v_cndmask_b32_e64 v34, v34, v35, s[0:1]
	v_cndmask_b32_e64 v35, v35, v36, s[0:1]
	v_cndmask_b32_e64 v36, v36, v37, s[0:1]
	v_cndmask_b32_e64 v37, v37, v31, s[0:1]
	v_cmp_eq_u32_e64 s[0:1], v38, v56
	v_cndmask_b32_e32 v22, v22, v24, vcc
	v_cndmask_b32_e32 v24, v24, v25, vcc
	v_cndmask_b32_e32 v25, v25, v26, vcc
	v_cndmask_b32_e32 v26, v26, v27, vcc
	v_cndmask_b32_e32 v27, v27, v28, vcc
	v_cndmask_b32_e32 v28, v28, v29, vcc
	v_cndmask_b32_e32 v29, v29, v23, vcc
	v_cmp_eq_u32_e32 vcc, s40, v171
	v_cndmask_b32_e64 v38, v38, v40, s[0:1]
	v_cndmask_b32_e64 v40, v40, v41, s[0:1]
	v_cndmask_b32_e64 v41, v41, v42, s[0:1]
	v_cndmask_b32_e64 v42, v42, v43, s[0:1]
	v_cndmask_b32_e64 v43, v43, v44, s[0:1]
	v_cndmask_b32_e64 v44, v44, v45, s[0:1]
	v_cndmask_b32_e64 v45, v45, v39, s[0:1]
	v_cmp_eq_u32_e64 s[0:1], v46, v57
	s_add_i32 s40, s40, 1
	v_cndmask_b32_e32 v18, v18, v54, vcc
	v_cndmask_b32_e32 v19, v19, v55, vcc
	v_cndmask_b32_e32 v20, v20, v56, vcc
	v_cndmask_b32_e64 v46, v46, v48, s[0:1]
	v_cndmask_b32_e64 v48, v48, v49, s[0:1]
	v_cndmask_b32_e64 v49, v49, v50, s[0:1]
	v_cndmask_b32_e64 v50, v50, v51, s[0:1]
	v_cndmask_b32_e64 v51, v51, v52, s[0:1]
	v_cndmask_b32_e64 v52, v52, v53, s[0:1]
	v_cndmask_b32_e64 v53, v53, v47, s[0:1]
	v_cndmask_b32_e32 v21, v21, v57, vcc
	v_max_u32_dpp v55, v30, v30 row_ror:1 row_mask:0xf bank_mask:0xf bound_ctrl:1
	v_max_u32_dpp v54, v22, v22 row_ror:1 row_mask:0xf bank_mask:0xf bound_ctrl:1
	v_max_u32_dpp v56, v38, v38 row_ror:1 row_mask:0xf bank_mask:0xf bound_ctrl:1
	v_max_u32_dpp v55, v55, v55 row_ror:2 row_mask:0xf bank_mask:0xf bound_ctrl:1
	v_max_u32_dpp v57, v46, v46 row_ror:1 row_mask:0xf bank_mask:0xf bound_ctrl:1
	v_max_u32_dpp v54, v54, v54 row_ror:2 row_mask:0xf bank_mask:0xf bound_ctrl:1
	v_max_u32_dpp v56, v56, v56 row_ror:2 row_mask:0xf bank_mask:0xf bound_ctrl:1
	v_max_u32_dpp v55, v55, v55 row_ror:4 row_mask:0xf bank_mask:0xf bound_ctrl:1
	v_max_u32_dpp v57, v57, v57 row_ror:2 row_mask:0xf bank_mask:0xf bound_ctrl:1
	v_max_u32_dpp v54, v54, v54 row_ror:4 row_mask:0xf bank_mask:0xf bound_ctrl:1
	v_max_u32_dpp v56, v56, v56 row_ror:4 row_mask:0xf bank_mask:0xf bound_ctrl:1
	v_max_u32_dpp v55, v55, v55 row_ror:8 row_mask:0xf bank_mask:0xf bound_ctrl:1
	v_max_u32_dpp v57, v57, v57 row_ror:4 row_mask:0xf bank_mask:0xf bound_ctrl:1
	v_max_u32_dpp v54, v54, v54 row_ror:8 row_mask:0xf bank_mask:0xf bound_ctrl:1
	v_max_u32_dpp v56, v56, v56 row_ror:8 row_mask:0xf bank_mask:0xf bound_ctrl:1
	v_cmp_eq_u32_e64 s[0:1], v30, v55
	v_max_u32_dpp v57, v57, v57 row_ror:8 row_mask:0xf bank_mask:0xf bound_ctrl:1
	v_cmp_eq_u32_e32 vcc, v22, v54
	v_cndmask_b32_e64 v30, v30, v32, s[0:1]
	v_cndmask_b32_e64 v32, v32, v33, s[0:1]
	v_cndmask_b32_e64 v33, v33, v34, s[0:1]
	v_cndmask_b32_e64 v34, v34, v35, s[0:1]
	v_cndmask_b32_e64 v35, v35, v36, s[0:1]
	v_cndmask_b32_e64 v36, v36, v37, s[0:1]
	v_cmp_eq_u32_e64 s[0:1], v38, v56
	v_cndmask_b32_e32 v22, v22, v24, vcc
	v_cndmask_b32_e32 v24, v24, v25, vcc
	v_cndmask_b32_e32 v25, v25, v26, vcc
	v_cndmask_b32_e32 v26, v26, v27, vcc
	v_cndmask_b32_e32 v27, v27, v28, vcc
	v_cndmask_b32_e32 v28, v28, v29, vcc
	v_cmp_eq_u32_e32 vcc, s40, v171
	v_cndmask_b32_e64 v38, v38, v40, s[0:1]
	v_cndmask_b32_e64 v40, v40, v41, s[0:1]
	v_cndmask_b32_e64 v41, v41, v42, s[0:1]
	v_cndmask_b32_e64 v42, v42, v43, s[0:1]
	v_cndmask_b32_e64 v43, v43, v44, s[0:1]
	v_cndmask_b32_e64 v44, v44, v45, s[0:1]
	v_cmp_eq_u32_e64 s[0:1], v46, v57
	s_add_i32 s40, s40, 1
	v_cndmask_b32_e32 v18, v18, v54, vcc
	v_cndmask_b32_e32 v19, v19, v55, vcc
	v_cndmask_b32_e32 v20, v20, v56, vcc
	v_cndmask_b32_e64 v46, v46, v48, s[0:1]
	v_cndmask_b32_e64 v48, v48, v49, s[0:1]
	v_cndmask_b32_e64 v49, v49, v50, s[0:1]
	v_cndmask_b32_e64 v50, v50, v51, s[0:1]
	v_cndmask_b32_e64 v51, v51, v52, s[0:1]
	v_cndmask_b32_e64 v52, v52, v53, s[0:1]
	v_cndmask_b32_e32 v21, v21, v57, vcc
	v_max_u32_dpp v55, v30, v30 row_ror:1 row_mask:0xf bank_mask:0xf bound_ctrl:1
	v_max_u32_dpp v54, v22, v22 row_ror:1 row_mask:0xf bank_mask:0xf bound_ctrl:1
	v_max_u32_dpp v56, v38, v38 row_ror:1 row_mask:0xf bank_mask:0xf bound_ctrl:1
	v_max_u32_dpp v55, v55, v55 row_ror:2 row_mask:0xf bank_mask:0xf bound_ctrl:1
	v_max_u32_dpp v57, v46, v46 row_ror:1 row_mask:0xf bank_mask:0xf bound_ctrl:1
	v_max_u32_dpp v54, v54, v54 row_ror:2 row_mask:0xf bank_mask:0xf bound_ctrl:1
	v_max_u32_dpp v56, v56, v56 row_ror:2 row_mask:0xf bank_mask:0xf bound_ctrl:1
	v_max_u32_dpp v55, v55, v55 row_ror:4 row_mask:0xf bank_mask:0xf bound_ctrl:1
	v_max_u32_dpp v57, v57, v57 row_ror:2 row_mask:0xf bank_mask:0xf bound_ctrl:1
	v_max_u32_dpp v54, v54, v54 row_ror:4 row_mask:0xf bank_mask:0xf bound_ctrl:1
	v_max_u32_dpp v56, v56, v56 row_ror:4 row_mask:0xf bank_mask:0xf bound_ctrl:1
	v_max_u32_dpp v55, v55, v55 row_ror:8 row_mask:0xf bank_mask:0xf bound_ctrl:1
	v_max_u32_dpp v57, v57, v57 row_ror:4 row_mask:0xf bank_mask:0xf bound_ctrl:1
	v_max_u32_dpp v54, v54, v54 row_ror:8 row_mask:0xf bank_mask:0xf bound_ctrl:1
	v_max_u32_dpp v56, v56, v56 row_ror:8 row_mask:0xf bank_mask:0xf bound_ctrl:1
	v_cmp_eq_u32_e64 s[0:1], v30, v55
	v_max_u32_dpp v57, v57, v57 row_ror:8 row_mask:0xf bank_mask:0xf bound_ctrl:1
	v_cmp_eq_u32_e32 vcc, v22, v54
	v_cndmask_b32_e64 v30, v30, v32, s[0:1]
	v_cndmask_b32_e64 v32, v32, v33, s[0:1]
	v_cndmask_b32_e64 v33, v33, v34, s[0:1]
	v_cndmask_b32_e64 v34, v34, v35, s[0:1]
	v_cndmask_b32_e64 v35, v35, v36, s[0:1]
	v_cmp_eq_u32_e64 s[0:1], v38, v56
	v_cndmask_b32_e32 v22, v22, v24, vcc
	v_cndmask_b32_e32 v24, v24, v25, vcc
	v_cndmask_b32_e32 v25, v25, v26, vcc
	v_cndmask_b32_e32 v26, v26, v27, vcc
	v_cndmask_b32_e32 v27, v27, v28, vcc
	v_cmp_eq_u32_e32 vcc, s40, v171
	v_cndmask_b32_e64 v38, v38, v40, s[0:1]
	v_cndmask_b32_e64 v40, v40, v41, s[0:1]
	v_cndmask_b32_e64 v41, v41, v42, s[0:1]
	v_cndmask_b32_e64 v42, v42, v43, s[0:1]
	v_cndmask_b32_e64 v43, v43, v44, s[0:1]
	v_cmp_eq_u32_e64 s[0:1], v46, v57
	s_add_i32 s40, s40, 1
	v_cndmask_b32_e32 v18, v18, v54, vcc
	v_cndmask_b32_e32 v19, v19, v55, vcc
	v_cndmask_b32_e32 v20, v20, v56, vcc
	v_cndmask_b32_e64 v46, v46, v48, s[0:1]
	v_cndmask_b32_e64 v48, v48, v49, s[0:1]
	v_cndmask_b32_e64 v49, v49, v50, s[0:1]
	v_cndmask_b32_e64 v50, v50, v51, s[0:1]
	v_cndmask_b32_e64 v51, v51, v52, s[0:1]
	v_cndmask_b32_e32 v21, v21, v57, vcc
	v_max_u32_dpp v55, v30, v30 row_ror:1 row_mask:0xf bank_mask:0xf bound_ctrl:1
	v_max_u32_dpp v54, v22, v22 row_ror:1 row_mask:0xf bank_mask:0xf bound_ctrl:1
	v_max_u32_dpp v56, v38, v38 row_ror:1 row_mask:0xf bank_mask:0xf bound_ctrl:1
	v_max_u32_dpp v55, v55, v55 row_ror:2 row_mask:0xf bank_mask:0xf bound_ctrl:1
	v_max_u32_dpp v57, v46, v46 row_ror:1 row_mask:0xf bank_mask:0xf bound_ctrl:1
	v_max_u32_dpp v54, v54, v54 row_ror:2 row_mask:0xf bank_mask:0xf bound_ctrl:1
	v_max_u32_dpp v56, v56, v56 row_ror:2 row_mask:0xf bank_mask:0xf bound_ctrl:1
	v_max_u32_dpp v55, v55, v55 row_ror:4 row_mask:0xf bank_mask:0xf bound_ctrl:1
	v_max_u32_dpp v57, v57, v57 row_ror:2 row_mask:0xf bank_mask:0xf bound_ctrl:1
	v_max_u32_dpp v54, v54, v54 row_ror:4 row_mask:0xf bank_mask:0xf bound_ctrl:1
	v_max_u32_dpp v56, v56, v56 row_ror:4 row_mask:0xf bank_mask:0xf bound_ctrl:1
	v_max_u32_dpp v55, v55, v55 row_ror:8 row_mask:0xf bank_mask:0xf bound_ctrl:1
	v_max_u32_dpp v57, v57, v57 row_ror:4 row_mask:0xf bank_mask:0xf bound_ctrl:1
	v_max_u32_dpp v54, v54, v54 row_ror:8 row_mask:0xf bank_mask:0xf bound_ctrl:1
	v_max_u32_dpp v56, v56, v56 row_ror:8 row_mask:0xf bank_mask:0xf bound_ctrl:1
	v_cmp_eq_u32_e64 s[0:1], v30, v55
	v_max_u32_dpp v57, v57, v57 row_ror:8 row_mask:0xf bank_mask:0xf bound_ctrl:1
	v_cmp_eq_u32_e32 vcc, v22, v54
	v_cndmask_b32_e64 v30, v30, v32, s[0:1]
	v_cndmask_b32_e64 v32, v32, v33, s[0:1]
	v_cndmask_b32_e64 v33, v33, v34, s[0:1]
	v_cndmask_b32_e64 v34, v34, v35, s[0:1]
	v_cmp_eq_u32_e64 s[0:1], v38, v56
	v_cndmask_b32_e32 v22, v22, v24, vcc
	v_cndmask_b32_e32 v24, v24, v25, vcc
	v_cndmask_b32_e32 v25, v25, v26, vcc
	v_cndmask_b32_e32 v26, v26, v27, vcc
	v_cmp_eq_u32_e32 vcc, s40, v171
	v_cndmask_b32_e64 v38, v38, v40, s[0:1]
	v_cndmask_b32_e64 v40, v40, v41, s[0:1]
	v_cndmask_b32_e64 v41, v41, v42, s[0:1]
	v_cndmask_b32_e64 v42, v42, v43, s[0:1]
	v_cmp_eq_u32_e64 s[0:1], v46, v57
	s_add_i32 s40, s40, 1
	v_cndmask_b32_e32 v18, v18, v54, vcc
	v_cndmask_b32_e32 v19, v19, v55, vcc
	v_cndmask_b32_e32 v20, v20, v56, vcc
	v_cndmask_b32_e64 v46, v46, v48, s[0:1]
	v_cndmask_b32_e64 v48, v48, v49, s[0:1]
	v_cndmask_b32_e64 v49, v49, v50, s[0:1]
	v_cndmask_b32_e64 v50, v50, v51, s[0:1]
	v_cndmask_b32_e32 v21, v21, v57, vcc
	v_max_u32_dpp v55, v30, v30 row_ror:1 row_mask:0xf bank_mask:0xf bound_ctrl:1
	v_max_u32_dpp v54, v22, v22 row_ror:1 row_mask:0xf bank_mask:0xf bound_ctrl:1
	v_max_u32_dpp v56, v38, v38 row_ror:1 row_mask:0xf bank_mask:0xf bound_ctrl:1
	v_max_u32_dpp v55, v55, v55 row_ror:2 row_mask:0xf bank_mask:0xf bound_ctrl:1
	v_max_u32_dpp v57, v46, v46 row_ror:1 row_mask:0xf bank_mask:0xf bound_ctrl:1
	v_max_u32_dpp v54, v54, v54 row_ror:2 row_mask:0xf bank_mask:0xf bound_ctrl:1
	v_max_u32_dpp v56, v56, v56 row_ror:2 row_mask:0xf bank_mask:0xf bound_ctrl:1
	v_max_u32_dpp v55, v55, v55 row_ror:4 row_mask:0xf bank_mask:0xf bound_ctrl:1
	v_max_u32_dpp v57, v57, v57 row_ror:2 row_mask:0xf bank_mask:0xf bound_ctrl:1
	v_max_u32_dpp v54, v54, v54 row_ror:4 row_mask:0xf bank_mask:0xf bound_ctrl:1
	v_max_u32_dpp v56, v56, v56 row_ror:4 row_mask:0xf bank_mask:0xf bound_ctrl:1
	v_max_u32_dpp v55, v55, v55 row_ror:8 row_mask:0xf bank_mask:0xf bound_ctrl:1
	v_max_u32_dpp v57, v57, v57 row_ror:4 row_mask:0xf bank_mask:0xf bound_ctrl:1
	v_max_u32_dpp v54, v54, v54 row_ror:8 row_mask:0xf bank_mask:0xf bound_ctrl:1
	v_max_u32_dpp v56, v56, v56 row_ror:8 row_mask:0xf bank_mask:0xf bound_ctrl:1
	v_cmp_eq_u32_e64 s[0:1], v30, v55
	v_max_u32_dpp v57, v57, v57 row_ror:8 row_mask:0xf bank_mask:0xf bound_ctrl:1
	v_cmp_eq_u32_e32 vcc, v22, v54
	v_cndmask_b32_e64 v30, v30, v32, s[0:1]
	v_cndmask_b32_e64 v32, v32, v33, s[0:1]
	v_cndmask_b32_e64 v33, v33, v34, s[0:1]
	v_cmp_eq_u32_e64 s[0:1], v38, v56
	v_cndmask_b32_e32 v22, v22, v24, vcc
	v_cndmask_b32_e32 v24, v24, v25, vcc
	v_cndmask_b32_e32 v25, v25, v26, vcc
	v_cmp_eq_u32_e32 vcc, s40, v171
	v_cndmask_b32_e64 v38, v38, v40, s[0:1]
	v_cndmask_b32_e64 v40, v40, v41, s[0:1]
	v_cndmask_b32_e64 v41, v41, v42, s[0:1]
	v_cmp_eq_u32_e64 s[0:1], v46, v57
	s_add_i32 s40, s40, 1
	v_cndmask_b32_e32 v18, v18, v54, vcc
	v_cndmask_b32_e32 v19, v19, v55, vcc
	v_cndmask_b32_e32 v20, v20, v56, vcc
	v_cndmask_b32_e64 v46, v46, v48, s[0:1]
	v_cndmask_b32_e64 v48, v48, v49, s[0:1]
	v_cndmask_b32_e64 v49, v49, v50, s[0:1]
	v_cndmask_b32_e32 v21, v21, v57, vcc
	v_max_u32_dpp v55, v30, v30 row_ror:1 row_mask:0xf bank_mask:0xf bound_ctrl:1
	v_max_u32_dpp v54, v22, v22 row_ror:1 row_mask:0xf bank_mask:0xf bound_ctrl:1
	v_max_u32_dpp v56, v38, v38 row_ror:1 row_mask:0xf bank_mask:0xf bound_ctrl:1
	v_max_u32_dpp v55, v55, v55 row_ror:2 row_mask:0xf bank_mask:0xf bound_ctrl:1
	v_max_u32_dpp v57, v46, v46 row_ror:1 row_mask:0xf bank_mask:0xf bound_ctrl:1
	v_max_u32_dpp v54, v54, v54 row_ror:2 row_mask:0xf bank_mask:0xf bound_ctrl:1
	v_max_u32_dpp v56, v56, v56 row_ror:2 row_mask:0xf bank_mask:0xf bound_ctrl:1
	v_max_u32_dpp v55, v55, v55 row_ror:4 row_mask:0xf bank_mask:0xf bound_ctrl:1
	v_max_u32_dpp v57, v57, v57 row_ror:2 row_mask:0xf bank_mask:0xf bound_ctrl:1
	v_max_u32_dpp v54, v54, v54 row_ror:4 row_mask:0xf bank_mask:0xf bound_ctrl:1
	v_max_u32_dpp v56, v56, v56 row_ror:4 row_mask:0xf bank_mask:0xf bound_ctrl:1
	v_max_u32_dpp v55, v55, v55 row_ror:8 row_mask:0xf bank_mask:0xf bound_ctrl:1
	v_max_u32_dpp v57, v57, v57 row_ror:4 row_mask:0xf bank_mask:0xf bound_ctrl:1
	v_max_u32_dpp v54, v54, v54 row_ror:8 row_mask:0xf bank_mask:0xf bound_ctrl:1
	v_max_u32_dpp v56, v56, v56 row_ror:8 row_mask:0xf bank_mask:0xf bound_ctrl:1
	v_cmp_eq_u32_e64 s[0:1], v30, v55
	v_max_u32_dpp v57, v57, v57 row_ror:8 row_mask:0xf bank_mask:0xf bound_ctrl:1
	v_cmp_eq_u32_e32 vcc, v22, v54
	v_cndmask_b32_e64 v30, v30, v32, s[0:1]
	v_cndmask_b32_e64 v32, v32, v33, s[0:1]
	v_cmp_eq_u32_e64 s[0:1], v38, v56
	v_cndmask_b32_e32 v22, v22, v24, vcc
	v_cndmask_b32_e32 v24, v24, v25, vcc
	v_cmp_eq_u32_e32 vcc, s40, v171
	v_cndmask_b32_e64 v38, v38, v40, s[0:1]
	v_cndmask_b32_e64 v40, v40, v41, s[0:1]
	v_cmp_eq_u32_e64 s[0:1], v46, v57
	s_add_i32 s40, s40, 1
	v_cndmask_b32_e32 v18, v18, v54, vcc
	v_cndmask_b32_e32 v19, v19, v55, vcc
	v_cndmask_b32_e32 v20, v20, v56, vcc
	v_cndmask_b32_e64 v46, v46, v48, s[0:1]
	v_cndmask_b32_e64 v48, v48, v49, s[0:1]
	v_cndmask_b32_e32 v21, v21, v57, vcc
	v_max_u32_dpp v55, v30, v30 row_ror:1 row_mask:0xf bank_mask:0xf bound_ctrl:1
	v_max_u32_dpp v54, v22, v22 row_ror:1 row_mask:0xf bank_mask:0xf bound_ctrl:1
	v_max_u32_dpp v56, v38, v38 row_ror:1 row_mask:0xf bank_mask:0xf bound_ctrl:1
	v_max_u32_dpp v55, v55, v55 row_ror:2 row_mask:0xf bank_mask:0xf bound_ctrl:1
	v_max_u32_dpp v57, v46, v46 row_ror:1 row_mask:0xf bank_mask:0xf bound_ctrl:1
	v_max_u32_dpp v54, v54, v54 row_ror:2 row_mask:0xf bank_mask:0xf bound_ctrl:1
	v_max_u32_dpp v56, v56, v56 row_ror:2 row_mask:0xf bank_mask:0xf bound_ctrl:1
	v_max_u32_dpp v55, v55, v55 row_ror:4 row_mask:0xf bank_mask:0xf bound_ctrl:1
	v_max_u32_dpp v57, v57, v57 row_ror:2 row_mask:0xf bank_mask:0xf bound_ctrl:1
	v_max_u32_dpp v54, v54, v54 row_ror:4 row_mask:0xf bank_mask:0xf bound_ctrl:1
	v_max_u32_dpp v56, v56, v56 row_ror:4 row_mask:0xf bank_mask:0xf bound_ctrl:1
	v_max_u32_dpp v55, v55, v55 row_ror:8 row_mask:0xf bank_mask:0xf bound_ctrl:1
	v_max_u32_dpp v57, v57, v57 row_ror:4 row_mask:0xf bank_mask:0xf bound_ctrl:1
	v_max_u32_dpp v54, v54, v54 row_ror:8 row_mask:0xf bank_mask:0xf bound_ctrl:1
	v_max_u32_dpp v56, v56, v56 row_ror:8 row_mask:0xf bank_mask:0xf bound_ctrl:1
	v_cmp_eq_u32_e64 s[0:1], v30, v55
	v_max_u32_dpp v57, v57, v57 row_ror:8 row_mask:0xf bank_mask:0xf bound_ctrl:1
	v_cmp_eq_u32_e32 vcc, v22, v54
	v_cndmask_b32_e64 v30, v30, v32, s[0:1]
	v_cmp_eq_u32_e64 s[0:1], v38, v56
	v_cndmask_b32_e32 v22, v22, v24, vcc
	v_cmp_eq_u32_e32 vcc, s40, v171
	v_cndmask_b32_e64 v38, v38, v40, s[0:1]
	v_cmp_eq_u32_e64 s[0:1], v46, v57
	s_add_i32 s40, s40, 1
	v_cndmask_b32_e32 v18, v18, v54, vcc
	v_cndmask_b32_e32 v19, v19, v55, vcc
	v_cndmask_b32_e32 v20, v20, v56, vcc
	v_cndmask_b32_e64 v46, v46, v48, s[0:1]
	v_cndmask_b32_e32 v21, v21, v57, vcc
	v_max_u32_dpp v55, v30, v30 row_ror:1 row_mask:0xf bank_mask:0xf bound_ctrl:1
	v_max_u32_dpp v54, v22, v22 row_ror:1 row_mask:0xf bank_mask:0xf bound_ctrl:1
	v_max_u32_dpp v56, v38, v38 row_ror:1 row_mask:0xf bank_mask:0xf bound_ctrl:1
	v_max_u32_dpp v55, v55, v55 row_ror:2 row_mask:0xf bank_mask:0xf bound_ctrl:1
	v_max_u32_dpp v57, v46, v46 row_ror:1 row_mask:0xf bank_mask:0xf bound_ctrl:1
	v_max_u32_dpp v54, v54, v54 row_ror:2 row_mask:0xf bank_mask:0xf bound_ctrl:1
	v_max_u32_dpp v56, v56, v56 row_ror:2 row_mask:0xf bank_mask:0xf bound_ctrl:1
	v_max_u32_dpp v55, v55, v55 row_ror:4 row_mask:0xf bank_mask:0xf bound_ctrl:1
	v_max_u32_dpp v57, v57, v57 row_ror:2 row_mask:0xf bank_mask:0xf bound_ctrl:1
	v_max_u32_dpp v54, v54, v54 row_ror:4 row_mask:0xf bank_mask:0xf bound_ctrl:1
	v_max_u32_dpp v56, v56, v56 row_ror:4 row_mask:0xf bank_mask:0xf bound_ctrl:1
	v_max_u32_dpp v55, v55, v55 row_ror:8 row_mask:0xf bank_mask:0xf bound_ctrl:1
	v_max_u32_dpp v57, v57, v57 row_ror:4 row_mask:0xf bank_mask:0xf bound_ctrl:1
	v_max_u32_dpp v54, v54, v54 row_ror:8 row_mask:0xf bank_mask:0xf bound_ctrl:1
	v_max_u32_dpp v56, v56, v56 row_ror:8 row_mask:0xf bank_mask:0xf bound_ctrl:1
	v_max_u32_dpp v57, v57, v57 row_ror:8 row_mask:0xf bank_mask:0xf bound_ctrl:1
	v_cmp_eq_u32_e32 vcc, s40, v171
	s_add_i32 s40, s40, 1
	s_nop 0
	v_cndmask_b32_e32 v18, v18, v54, vcc
	v_cndmask_b32_e32 v19, v19, v55, vcc
	v_cndmask_b32_e32 v20, v20, v56, vcc
	v_cndmask_b32_e32 v21, v21, v57, vcc
	ds_read_b128 v[22:25], v184 offset:34816
	ds_read_b128 v[26:29], v184 offset:34880
	s_waitcnt vmcnt(0) lgkmcnt(1)
	v_mfma_f32_16x16x32_bf16 v[22:25], v[12:15], v[22:25], 0
	s_waitcnt lgkmcnt(0)
	v_mfma_f32_16x16x32_bf16 v[22:25], v[8:11], v[26:29], v[22:25]
	ds_read_b128 v[26:29], v184 offset:34944
	s_waitcnt lgkmcnt(0)
	v_mfma_f32_16x16x32_bf16 v[22:25], v[4:7], v[26:29], v[22:25]
	ds_read_b128 v[26:29], v184 offset:35008
	s_waitcnt lgkmcnt(0)
	v_mfma_f32_16x16x32_bf16 v[22:25], v[0:3], v[26:29], v[22:25]
	ds_read_b128 v[26:29], v184 offset:39168
	ds_read_b128 v[30:33], v184 offset:39232
	s_waitcnt lgkmcnt(1)
	v_mfma_f32_16x16x32_bf16 v[26:29], v[12:15], v[26:29], 0
	s_waitcnt lgkmcnt(0)
	v_mfma_f32_16x16x32_bf16 v[26:29], v[8:11], v[30:33], v[26:29]
	ds_read_b128 v[30:33], v184 offset:39296
	ds_read_b128 v[34:37], v184 offset:39360
	s_waitcnt lgkmcnt(1)
	v_mfma_f32_16x16x32_bf16 v[26:29], v[4:7], v[30:33], v[26:29]
	s_waitcnt lgkmcnt(0)
	v_mfma_f32_16x16x32_bf16 v[26:29], v[0:3], v[34:37], v[26:29]
	ds_read_b128 v[30:33], v184 offset:43520
	ds_read_b128 v[34:37], v184 offset:43584
	s_waitcnt lgkmcnt(1)
	v_mfma_f32_16x16x32_bf16 v[30:33], v[12:15], v[30:33], 0
	s_waitcnt lgkmcnt(0)
	v_mfma_f32_16x16x32_bf16 v[30:33], v[8:11], v[34:37], v[30:33]
	ds_read_b128 v[34:37], v184 offset:43648
	ds_read_b128 v[38:41], v184 offset:43712
	s_waitcnt lgkmcnt(1)
	v_mfma_f32_16x16x32_bf16 v[30:33], v[4:7], v[34:37], v[30:33]
	s_waitcnt lgkmcnt(0)
	v_mfma_f32_16x16x32_bf16 v[30:33], v[0:3], v[38:41], v[30:33]
	ds_read_b128 v[34:37], v184 offset:47872
	ds_read_b128 v[38:41], v184 offset:47936
	s_waitcnt lgkmcnt(1)
	v_mfma_f32_16x16x32_bf16 v[34:37], v[12:15], v[34:37], 0
	s_waitcnt lgkmcnt(0)
	v_mfma_f32_16x16x32_bf16 v[34:37], v[8:11], v[38:41], v[34:37]
	ds_read_b128 v[38:41], v184 offset:48000
	ds_read_b128 v[42:45], v184 offset:48064
	s_waitcnt lgkmcnt(1)
	v_mfma_f32_16x16x32_bf16 v[34:37], v[4:7], v[38:41], v[34:37]
	s_waitcnt lgkmcnt(0)
	v_mfma_f32_16x16x32_bf16 v[34:37], v[0:3], v[42:45], v[34:37]
	ds_read_b128 v[38:41], v184 offset:52224
	ds_read_b128 v[42:45], v184 offset:52288
	s_waitcnt lgkmcnt(1)
	v_mfma_f32_16x16x32_bf16 v[38:41], v[12:15], v[38:41], 0
	s_waitcnt lgkmcnt(0)
	v_mfma_f32_16x16x32_bf16 v[38:41], v[8:11], v[42:45], v[38:41]
	ds_read_b128 v[42:45], v184 offset:52352
	ds_read_b128 v[46:49], v184 offset:52416
	s_waitcnt lgkmcnt(1)
	v_mfma_f32_16x16x32_bf16 v[38:41], v[4:7], v[42:45], v[38:41]
	s_waitcnt lgkmcnt(0)
	v_mfma_f32_16x16x32_bf16 v[38:41], v[0:3], v[46:49], v[38:41]
	ds_read_b128 v[42:45], v184 offset:56576
	ds_read_b128 v[46:49], v184 offset:56640
	s_waitcnt lgkmcnt(1)
	v_mfma_f32_16x16x32_bf16 v[42:45], v[12:15], v[42:45], 0
	s_waitcnt lgkmcnt(0)
	v_mfma_f32_16x16x32_bf16 v[42:45], v[8:11], v[46:49], v[42:45]
	ds_read_b128 v[46:49], v184 offset:56704
	ds_read_b128 v[50:53], v184 offset:56768
	s_waitcnt lgkmcnt(1)
	v_mfma_f32_16x16x32_bf16 v[42:45], v[4:7], v[46:49], v[42:45]
	s_waitcnt lgkmcnt(0)
	v_mfma_f32_16x16x32_bf16 v[42:45], v[0:3], v[50:53], v[42:45]
	ds_read_b128 v[46:49], v184 offset:60928
	ds_read_b128 v[50:53], v184 offset:60992
	s_waitcnt lgkmcnt(1)
	v_mfma_f32_16x16x32_bf16 v[46:49], v[12:15], v[46:49], 0
	s_waitcnt lgkmcnt(0)
	v_mfma_f32_16x16x32_bf16 v[46:49], v[8:11], v[50:53], v[46:49]
	ds_read_b128 v[50:53], v184 offset:61056
	ds_read_b128 v[54:57], v184 offset:61120
	s_waitcnt lgkmcnt(1)
	v_mfma_f32_16x16x32_bf16 v[46:49], v[4:7], v[50:53], v[46:49]
	s_waitcnt lgkmcnt(0)
	v_mfma_f32_16x16x32_bf16 v[46:49], v[0:3], v[54:57], v[46:49]
	ds_read_b128 v[50:53], v184 offset:65280
	ds_read_b128 v[54:57], v184 offset:65344
	s_waitcnt lgkmcnt(1)
	v_mfma_f32_16x16x32_bf16 v[12:15], v[12:15], v[50:53], 0
	s_waitcnt lgkmcnt(0)
	v_mfma_f32_16x16x32_bf16 v[8:11], v[8:11], v[54:57], v[12:15]
	s_nop 5
	ds_read_b128 v[12:15], v184 offset:65408
	ds_read_b128 v[50:53], v184 offset:65472
	s_waitcnt lgkmcnt(1)
	v_mfma_f32_16x16x32_bf16 v[4:7], v[4:7], v[12:15], v[8:11]
	s_waitcnt lgkmcnt(0)
	v_mfma_f32_16x16x32_bf16 v[0:3], v[0:3], v[50:53], v[4:7]
	s_nop 7
	v_cmp_lt_i32_e32 vcc, -1, v3
	s_mov_b32 s40, 0
	s_nop 0
	v_cndmask_b32_e32 v4, -1, v217, vcc
	v_cmp_lt_i32_e32 vcc, -1, v49
	v_xor_b32_e32 v3, v4, v3
	v_and_or_b32 v3, v3, s67, v178
	v_cndmask_b32_e32 v4, -1, v217, vcc
	v_xor_b32_e32 v4, v4, v49
	v_cmp_lt_i32_e32 vcc, -1, v45
	v_and_or_b32 v49, v4, s67, v177
	s_nop 0
	v_cndmask_b32_e32 v4, -1, v217, vcc
	v_xor_b32_e32 v4, v4, v45
	v_cmp_lt_i32_e32 vcc, -1, v41
	v_and_or_b32 v45, v4, s67, v176
	s_nop 0
	v_cndmask_b32_e32 v4, -1, v217, vcc
	v_xor_b32_e32 v4, v4, v41
	v_cmp_lt_i32_e32 vcc, -1, v37
	v_and_or_b32 v41, v4, s67, v175
	s_nop 0
	v_cndmask_b32_e32 v4, -1, v217, vcc
	v_xor_b32_e32 v4, v4, v37
	v_cmp_lt_i32_e32 vcc, -1, v33
	v_and_or_b32 v37, v4, s67, v170
	s_nop 0
	v_cndmask_b32_e32 v4, -1, v217, vcc
	v_xor_b32_e32 v4, v4, v33
	v_cmp_lt_i32_e32 vcc, -1, v29
	v_and_or_b32 v50, v4, s67, v181
	s_nop 0
	v_cndmask_b32_e32 v4, -1, v217, vcc
	v_xor_b32_e32 v4, v4, v29
	v_cmp_lt_i32_e32 vcc, -1, v25
	v_and_or_b32 v51, v4, s67, v180
	s_nop 0
	v_cndmask_b32_e32 v4, -1, v217, vcc
	v_xor_b32_e32 v4, v4, v25
	v_cmp_lt_i32_e32 vcc, -1, v2
	v_and_or_b32 v52, v4, s67, v179
	s_nop 0
	v_cndmask_b32_e32 v4, -1, v217, vcc
	v_cmp_lt_i32_e32 vcc, -1, v48
	v_xor_b32_e32 v2, v4, v2
	v_and_or_b32 v2, v2, s67, v178
	v_cndmask_b32_e32 v4, -1, v217, vcc
	v_xor_b32_e32 v4, v4, v48
	v_cmp_lt_i32_e32 vcc, -1, v44
	v_and_or_b32 v29, v4, s67, v177
	s_nop 0
	v_cndmask_b32_e32 v4, -1, v217, vcc
	v_xor_b32_e32 v4, v4, v44
	v_cmp_lt_i32_e32 vcc, -1, v40
	v_and_or_b32 v33, v4, s67, v176
	s_nop 0
	v_cndmask_b32_e32 v4, -1, v217, vcc
	v_xor_b32_e32 v4, v4, v40
	v_cmp_lt_i32_e32 vcc, -1, v36
	v_and_or_b32 v40, v4, s67, v175
	s_nop 0
	v_cndmask_b32_e32 v4, -1, v217, vcc
	v_xor_b32_e32 v4, v4, v36
	v_cmp_lt_i32_e32 vcc, -1, v32
	v_and_or_b32 v36, v4, s67, v170
	s_nop 0
	v_cndmask_b32_e32 v4, -1, v217, vcc
	v_xor_b32_e32 v4, v4, v32
	v_cmp_lt_i32_e32 vcc, -1, v28
	v_and_or_b32 v32, v4, s67, v181
	s_nop 0
	v_cndmask_b32_e32 v4, -1, v217, vcc
	v_xor_b32_e32 v4, v4, v28
	v_cmp_lt_i32_e32 vcc, -1, v24
	v_and_or_b32 v28, v4, s67, v180
	s_nop 0
	v_cndmask_b32_e32 v4, -1, v217, vcc
	v_xor_b32_e32 v4, v4, v24
	v_cmp_lt_i32_e32 vcc, -1, v1
	v_and_or_b32 v44, v4, s67, v179
	s_nop 0
	v_cndmask_b32_e32 v4, -1, v217, vcc
	v_cmp_lt_i32_e32 vcc, -1, v47
	v_xor_b32_e32 v1, v4, v1
	v_and_or_b32 v1, v1, s67, v178
	v_cndmask_b32_e32 v4, -1, v217, vcc
	v_xor_b32_e32 v4, v4, v47
	v_cmp_lt_i32_e32 vcc, -1, v43
	v_and_or_b32 v12, v4, s67, v177
	s_nop 0
	v_cndmask_b32_e32 v4, -1, v217, vcc
	v_xor_b32_e32 v4, v4, v43
	v_cmp_lt_i32_e32 vcc, -1, v39
	v_and_or_b32 v13, v4, s67, v176
	s_nop 0
	v_cndmask_b32_e32 v4, -1, v217, vcc
	v_xor_b32_e32 v4, v4, v39
	v_cmp_lt_i32_e32 vcc, -1, v35
	v_and_or_b32 v14, v4, s67, v175
	s_nop 0
	v_cndmask_b32_e32 v4, -1, v217, vcc
	v_xor_b32_e32 v4, v4, v35
	v_cmp_lt_i32_e32 vcc, -1, v31
	v_and_or_b32 v15, v4, s67, v170
	v_max_u32_e32 v35, v41, v45
	v_cndmask_b32_e32 v4, -1, v217, vcc
	v_xor_b32_e32 v4, v4, v31
	v_cmp_lt_i32_e32 vcc, -1, v27
	v_and_or_b32 v24, v4, s67, v181
	v_max_u32_e32 v31, v29, v2
	v_cndmask_b32_e32 v4, -1, v217, vcc
	v_xor_b32_e32 v4, v4, v27
	v_cmp_lt_i32_e32 vcc, -1, v23
	v_and_or_b32 v25, v4, s67, v180
	v_min_u32_e32 v2, v29, v2
	v_cndmask_b32_e32 v4, -1, v217, vcc
	v_xor_b32_e32 v4, v4, v23
	v_cmp_lt_i32_e32 vcc, -1, v0
	v_and_or_b32 v23, v4, s67, v179
	s_nop 0
	v_cndmask_b32_e32 v4, -1, v217, vcc
	v_cmp_lt_i32_e32 vcc, -1, v46
	v_xor_b32_e32 v0, v4, v0
	v_and_or_b32 v0, v0, s67, v178
	v_cndmask_b32_e32 v4, -1, v217, vcc
	v_cmp_lt_i32_e32 vcc, -1, v42
	v_xor_b32_e32 v4, v4, v46
	v_and_or_b32 v4, v4, s67, v177
	v_cndmask_b32_e32 v5, -1, v217, vcc
	v_cmp_lt_i32_e32 vcc, -1, v38
	v_xor_b32_e32 v5, v5, v42
	v_and_or_b32 v5, v5, s67, v176
	v_cndmask_b32_e32 v6, -1, v217, vcc
	v_cmp_lt_i32_e32 vcc, -1, v34
	v_xor_b32_e32 v6, v6, v38
	v_and_or_b32 v6, v6, s67, v175
	v_cndmask_b32_e32 v7, -1, v217, vcc
	v_cmp_lt_i32_e32 vcc, -1, v30
	v_xor_b32_e32 v7, v7, v34
	v_and_or_b32 v7, v7, s67, v170
	v_cndmask_b32_e32 v8, -1, v217, vcc
	v_cmp_lt_i32_e32 vcc, -1, v26
	v_xor_b32_e32 v8, v8, v30
	v_and_or_b32 v8, v8, s67, v181
	v_cndmask_b32_e32 v9, -1, v217, vcc
	v_cmp_lt_i32_e32 vcc, -1, v22
	v_xor_b32_e32 v9, v9, v26
	v_and_or_b32 v9, v9, s67, v180
	v_cndmask_b32_e32 v10, -1, v217, vcc
	v_xor_b32_e32 v10, v10, v22
	v_and_or_b32 v10, v10, s67, v179
	v_max_u32_e32 v11, v10, v9
	v_min_u32_e32 v9, v10, v9
	v_max_u32_e32 v10, v8, v7
	v_min_u32_e32 v7, v8, v7
	v_max_u32_e32 v8, v6, v5
	v_min_u32_e32 v5, v6, v5
	v_max_u32_e32 v6, v4, v0
	v_min_u32_e32 v0, v4, v0
	v_max_u32_e32 v22, v11, v10
	v_min_u32_e32 v4, v11, v10
	v_max_u32_e32 v10, v9, v7
	v_min_u32_e32 v7, v9, v7
	v_max_u32_e32 v9, v8, v6
	v_min_u32_e32 v6, v8, v6
	v_max_u32_e32 v8, v5, v0
	v_min_u32_e32 v0, v5, v0
	v_max_u32_e32 v5, v10, v4
	v_min_u32_e32 v10, v10, v4
	v_max_u32_e32 v11, v8, v6
	v_min_u32_e32 v6, v8, v6
	v_max_u32_e32 v4, v22, v9
	v_min_u32_e32 v8, v22, v9
	v_max_u32_e32 v9, v5, v11
	v_min_u32_e32 v11, v5, v11
	v_max_u32_e32 v22, v10, v6
	v_min_u32_e32 v26, v10, v6
	v_max_u32_e32 v6, v7, v0
	v_min_u32_e32 v5, v7, v0
	v_max_u32_e32 v0, v22, v8
	v_min_u32_e32 v10, v22, v8
	v_max_u32_e32 v22, v6, v11
	v_min_u32_e32 v11, v6, v11
	v_max_u32_e32 v6, v9, v0
	v_min_u32_e32 v7, v9, v0
	v_max_u32_e32 v8, v22, v10
	v_min_u32_e32 v9, v22, v10
	v_max_u32_e32 v0, v23, v25
	v_min_u32_e32 v22, v23, v25
	v_max_u32_e32 v23, v24, v15
	v_min_u32_e32 v15, v24, v15
	v_max_u32_e32 v24, v14, v13
	v_min_u32_e32 v13, v14, v13
	v_max_u32_e32 v14, v12, v1
	v_min_u32_e32 v1, v12, v1
	v_max_u32_e32 v25, v0, v23
	v_min_u32_e32 v0, v0, v23
	v_max_u32_e32 v12, v22, v15
	v_min_u32_e32 v15, v22, v15
	v_max_u32_e32 v22, v24, v14
	v_min_u32_e32 v14, v24, v14
	v_max_u32_e32 v23, v13, v1
	v_min_u32_e32 v1, v13, v1
	v_max_u32_e32 v13, v12, v0
	v_min_u32_e32 v0, v12, v0
	v_max_u32_e32 v24, v23, v14
	v_min_u32_e32 v14, v23, v14
	v_max_u32_e32 v12, v25, v22
	v_min_u32_e32 v22, v25, v22
	v_max_u32_e32 v23, v13, v24
	v_min_u32_e32 v24, v13, v24
	v_max_u32_e32 v25, v0, v14
	v_min_u32_e32 v0, v0, v14
	v_max_u32_e32 v14, v15, v1
	v_max_u32_e32 v10, v11, v26
	v_min_u32_e32 v11, v11, v26
	v_min_u32_e32 v13, v15, v1
	v_max_u32_e32 v1, v25, v22
	v_min_u32_e32 v25, v25, v22
	v_max_u32_e32 v26, v14, v24
	v_min_u32_e32 v27, v14, v24
	v_max_u32_e32 v14, v23, v1
	v_min_u32_e32 v15, v23, v1
	v_max_u32_e32 v22, v26, v25
	v_min_u32_e32 v23, v26, v25
	v_max_u32_e32 v24, v27, v0
	v_min_u32_e32 v25, v27, v0
	v_max_u32_e32 v0, v44, v28
	v_min_u32_e32 v1, v44, v28
	v_max_u32_e32 v26, v32, v36
	v_min_u32_e32 v27, v32, v36
	v_max_u32_e32 v28, v40, v33
	v_min_u32_e32 v30, v40, v33
	v_max_u32_e32 v29, v0, v26
	v_min_u32_e32 v0, v0, v26
	v_max_u32_e32 v26, v1, v27
	v_min_u32_e32 v1, v1, v27
	v_max_u32_e32 v27, v28, v31
	v_min_u32_e32 v28, v28, v31
	v_max_u32_e32 v31, v30, v2
	v_min_u32_e32 v2, v30, v2
	v_max_u32_e32 v30, v26, v0
	v_min_u32_e32 v0, v26, v0
	v_max_u32_e32 v32, v31, v28
	v_min_u32_e32 v28, v31, v28
	v_max_u32_e32 v26, v29, v27
	v_min_u32_e32 v29, v29, v27
	v_max_u32_e32 v31, v30, v32
	v_min_u32_e32 v30, v30, v32
	v_max_u32_e32 v32, v0, v28
	v_min_u32_e32 v0, v0, v28
	v_max_u32_e32 v28, v1, v2
	v_min_u32_e32 v27, v1, v2
	v_max_u32_e32 v1, v32, v29
	v_min_u32_e32 v2, v32, v29
	v_max_u32_e32 v32, v28, v30
	v_min_u32_e32 v33, v28, v30
	v_max_u32_e32 v28, v31, v1
	v_min_u32_e32 v29, v31, v1
	v_max_u32_e32 v30, v32, v2
	v_min_u32_e32 v31, v32, v2
	v_max_u32_e32 v32, v33, v0
	v_min_u32_e32 v33, v33, v0
	v_max_u32_e32 v0, v52, v51
	v_min_u32_e32 v1, v52, v51
	v_max_u32_e32 v2, v50, v37
	v_min_u32_e32 v34, v50, v37
	v_min_u32_e32 v36, v41, v45
	v_max_u32_e32 v37, v49, v3
	v_min_u32_e32 v3, v49, v3
	v_max_u32_e32 v38, v0, v2
	v_min_u32_e32 v0, v0, v2
	v_max_u32_e32 v2, v1, v34
	v_min_u32_e32 v1, v1, v34
	v_max_u32_e32 v39, v35, v37
	v_min_u32_e32 v34, v35, v37
	v_max_u32_e32 v35, v36, v3
	v_min_u32_e32 v3, v36, v3
	v_max_u32_e32 v36, v2, v0
	v_min_u32_e32 v0, v2, v0
	v_max_u32_e32 v2, v35, v34
	v_min_u32_e32 v35, v35, v34
	v_max_u32_e32 v34, v38, v39
	v_min_u32_e32 v37, v38, v39
	v_max_u32_e32 v38, v36, v2
	v_min_u32_e32 v2, v36, v2
	v_max_u32_e32 v36, v0, v35
	v_max_u32_e32 v39, v1, v3
	v_min_u32_e32 v0, v0, v35
	v_min_u32_e32 v35, v1, v3
	v_max_u32_e32 v1, v36, v37
	v_min_u32_e32 v3, v36, v37
	v_max_u32_e32 v40, v39, v2
	v_min_u32_e32 v2, v39, v2
	v_max_u32_e32 v36, v38, v1
	v_min_u32_e32 v37, v38, v1
	v_max_u32_e32 v38, v40, v3
	v_min_u32_e32 v39, v40, v3
	v_max_u32_e32 v40, v2, v0
	v_min_u32_e32 v41, v2, v0
	v_mov_b32_e32 v0, 0
	v_mov_b32_e32 v1, 0
	v_mov_b32_e32 v2, 0
	v_mov_b32_e32 v3, 0
.LBB0_1349:
	v_max_u32_dpp v43, v12, v12 row_ror:1 row_mask:0xf bank_mask:0xf bound_ctrl:1
	v_max_u32_dpp v42, v4, v4 row_ror:1 row_mask:0xf bank_mask:0xf bound_ctrl:1
	v_max_u32_dpp v44, v26, v26 row_ror:1 row_mask:0xf bank_mask:0xf bound_ctrl:1
	v_max_u32_dpp v43, v43, v43 row_ror:2 row_mask:0xf bank_mask:0xf bound_ctrl:1
	v_max_u32_dpp v45, v34, v34 row_ror:1 row_mask:0xf bank_mask:0xf bound_ctrl:1
	v_max_u32_dpp v42, v42, v42 row_ror:2 row_mask:0xf bank_mask:0xf bound_ctrl:1
	v_max_u32_dpp v44, v44, v44 row_ror:2 row_mask:0xf bank_mask:0xf bound_ctrl:1
	v_max_u32_dpp v43, v43, v43 row_ror:4 row_mask:0xf bank_mask:0xf bound_ctrl:1
	v_max_u32_dpp v45, v45, v45 row_ror:2 row_mask:0xf bank_mask:0xf bound_ctrl:1
	v_max_u32_dpp v42, v42, v42 row_ror:4 row_mask:0xf bank_mask:0xf bound_ctrl:1
	v_max_u32_dpp v44, v44, v44 row_ror:4 row_mask:0xf bank_mask:0xf bound_ctrl:1
	v_max_u32_dpp v43, v43, v43 row_ror:8 row_mask:0xf bank_mask:0xf bound_ctrl:1
	v_max_u32_dpp v45, v45, v45 row_ror:4 row_mask:0xf bank_mask:0xf bound_ctrl:1
	v_max_u32_dpp v42, v42, v42 row_ror:8 row_mask:0xf bank_mask:0xf bound_ctrl:1
	v_max_u32_dpp v44, v44, v44 row_ror:8 row_mask:0xf bank_mask:0xf bound_ctrl:1
	v_cmp_eq_u32_e64 s[0:1], v12, v43
	v_max_u32_dpp v45, v45, v45 row_ror:8 row_mask:0xf bank_mask:0xf bound_ctrl:1
	v_cmp_eq_u32_e32 vcc, v4, v42
	v_cndmask_b32_e64 v12, v12, v14, s[0:1]
	v_cndmask_b32_e64 v14, v14, v15, s[0:1]
	v_cndmask_b32_e64 v15, v15, v22, s[0:1]
	v_cndmask_b32_e64 v22, v22, v23, s[0:1]
	v_cndmask_b32_e64 v23, v23, v24, s[0:1]
	v_cndmask_b32_e64 v24, v24, v25, s[0:1]
	v_cndmask_b32_e64 v25, v25, v13, s[0:1]
	v_cndmask_b32_e64 v13, v13, 0, s[0:1]
	v_cmp_eq_u32_e64 s[0:1], v26, v44
	v_cndmask_b32_e32 v4, v4, v6, vcc
	v_cndmask_b32_e32 v6, v6, v7, vcc
	v_cndmask_b32_e32 v7, v7, v8, vcc
	v_cndmask_b32_e32 v8, v8, v9, vcc
	v_cndmask_b32_e32 v9, v9, v10, vcc
	v_cndmask_b32_e32 v10, v10, v11, vcc
	v_cndmask_b32_e32 v11, v11, v5, vcc
	v_cndmask_b32_e64 v5, v5, 0, vcc
	v_cmp_eq_u32_e32 vcc, s40, v171
	v_cndmask_b32_e64 v26, v26, v28, s[0:1]
	v_cndmask_b32_e64 v28, v28, v29, s[0:1]
	v_cndmask_b32_e64 v29, v29, v30, s[0:1]
	v_cndmask_b32_e64 v30, v30, v31, s[0:1]
	v_cndmask_b32_e64 v31, v31, v32, s[0:1]
	v_cndmask_b32_e64 v32, v32, v33, s[0:1]
	v_cndmask_b32_e64 v33, v33, v27, s[0:1]
	v_cndmask_b32_e64 v27, v27, 0, s[0:1]
	v_cmp_eq_u32_e64 s[0:1], v34, v45
	s_add_i32 s40, s40, 1
	v_cndmask_b32_e32 v0, v0, v42, vcc
	v_cndmask_b32_e32 v1, v1, v43, vcc
	v_cndmask_b32_e32 v2, v2, v44, vcc
	v_cndmask_b32_e64 v34, v34, v36, s[0:1]
	v_cndmask_b32_e64 v36, v36, v37, s[0:1]
	v_cndmask_b32_e64 v37, v37, v38, s[0:1]
	v_cndmask_b32_e64 v38, v38, v39, s[0:1]
	v_cndmask_b32_e64 v39, v39, v40, s[0:1]
	v_cndmask_b32_e64 v40, v40, v41, s[0:1]
	v_cndmask_b32_e64 v41, v41, v35, s[0:1]
	v_cndmask_b32_e64 v35, v35, 0, s[0:1]
	s_cmp_lg_u32 s40, 8
	v_cndmask_b32_e32 v3, v3, v45, vcc
	s_cbranch_scc1 .LBB0_1349
	v_max_u32_dpp v43, v12, v12 row_ror:1 row_mask:0xf bank_mask:0xf bound_ctrl:1
	v_max_u32_dpp v42, v4, v4 row_ror:1 row_mask:0xf bank_mask:0xf bound_ctrl:1
	v_max_u32_dpp v44, v26, v26 row_ror:1 row_mask:0xf bank_mask:0xf bound_ctrl:1
	v_max_u32_dpp v43, v43, v43 row_ror:2 row_mask:0xf bank_mask:0xf bound_ctrl:1
	v_max_u32_dpp v45, v34, v34 row_ror:1 row_mask:0xf bank_mask:0xf bound_ctrl:1
	v_max_u32_dpp v42, v42, v42 row_ror:2 row_mask:0xf bank_mask:0xf bound_ctrl:1
	v_max_u32_dpp v44, v44, v44 row_ror:2 row_mask:0xf bank_mask:0xf bound_ctrl:1
	v_max_u32_dpp v43, v43, v43 row_ror:4 row_mask:0xf bank_mask:0xf bound_ctrl:1
	v_max_u32_dpp v45, v45, v45 row_ror:2 row_mask:0xf bank_mask:0xf bound_ctrl:1
	v_max_u32_dpp v42, v42, v42 row_ror:4 row_mask:0xf bank_mask:0xf bound_ctrl:1
	v_max_u32_dpp v44, v44, v44 row_ror:4 row_mask:0xf bank_mask:0xf bound_ctrl:1
	v_max_u32_dpp v43, v43, v43 row_ror:8 row_mask:0xf bank_mask:0xf bound_ctrl:1
	v_max_u32_dpp v45, v45, v45 row_ror:4 row_mask:0xf bank_mask:0xf bound_ctrl:1
	v_max_u32_dpp v42, v42, v42 row_ror:8 row_mask:0xf bank_mask:0xf bound_ctrl:1
	v_max_u32_dpp v44, v44, v44 row_ror:8 row_mask:0xf bank_mask:0xf bound_ctrl:1
	v_cmp_eq_u32_e64 s[0:1], v12, v43
	v_max_u32_dpp v45, v45, v45 row_ror:8 row_mask:0xf bank_mask:0xf bound_ctrl:1
	v_cmp_eq_u32_e32 vcc, v4, v42
	v_cndmask_b32_e64 v12, v12, v14, s[0:1]
	v_cndmask_b32_e64 v14, v14, v15, s[0:1]
	v_cndmask_b32_e64 v15, v15, v22, s[0:1]
	v_cndmask_b32_e64 v22, v22, v23, s[0:1]
	v_cndmask_b32_e64 v23, v23, v24, s[0:1]
	v_cndmask_b32_e64 v24, v24, v25, s[0:1]
	v_cndmask_b32_e64 v25, v25, v13, s[0:1]
	v_cmp_eq_u32_e64 s[0:1], v26, v44
	v_cndmask_b32_e32 v4, v4, v6, vcc
	v_cndmask_b32_e32 v6, v6, v7, vcc
	v_cndmask_b32_e32 v7, v7, v8, vcc
	v_cndmask_b32_e32 v8, v8, v9, vcc
	v_cndmask_b32_e32 v9, v9, v10, vcc
	v_cndmask_b32_e32 v10, v10, v11, vcc
	v_cndmask_b32_e32 v11, v11, v5, vcc
	v_cmp_eq_u32_e32 vcc, s40, v171
	v_cndmask_b32_e64 v26, v26, v28, s[0:1]
	v_cndmask_b32_e64 v28, v28, v29, s[0:1]
	v_cndmask_b32_e64 v29, v29, v30, s[0:1]
	v_cndmask_b32_e64 v30, v30, v31, s[0:1]
	v_cndmask_b32_e64 v31, v31, v32, s[0:1]
	v_cndmask_b32_e64 v32, v32, v33, s[0:1]
	v_cndmask_b32_e64 v33, v33, v27, s[0:1]
	v_cmp_eq_u32_e64 s[0:1], v34, v45
	s_add_i32 s40, s40, 1
	v_cndmask_b32_e32 v0, v0, v42, vcc
	v_cndmask_b32_e32 v1, v1, v43, vcc
	v_cndmask_b32_e32 v2, v2, v44, vcc
	v_cndmask_b32_e64 v34, v34, v36, s[0:1]
	v_cndmask_b32_e64 v36, v36, v37, s[0:1]
	v_cndmask_b32_e64 v37, v37, v38, s[0:1]
	v_cndmask_b32_e64 v38, v38, v39, s[0:1]
	v_cndmask_b32_e64 v39, v39, v40, s[0:1]
	v_cndmask_b32_e64 v40, v40, v41, s[0:1]
	v_cndmask_b32_e64 v41, v41, v35, s[0:1]
	v_cndmask_b32_e32 v3, v3, v45, vcc
	v_max_u32_dpp v43, v12, v12 row_ror:1 row_mask:0xf bank_mask:0xf bound_ctrl:1
	v_max_u32_dpp v42, v4, v4 row_ror:1 row_mask:0xf bank_mask:0xf bound_ctrl:1
	v_max_u32_dpp v44, v26, v26 row_ror:1 row_mask:0xf bank_mask:0xf bound_ctrl:1
	v_max_u32_dpp v43, v43, v43 row_ror:2 row_mask:0xf bank_mask:0xf bound_ctrl:1
	v_max_u32_dpp v45, v34, v34 row_ror:1 row_mask:0xf bank_mask:0xf bound_ctrl:1
	v_max_u32_dpp v42, v42, v42 row_ror:2 row_mask:0xf bank_mask:0xf bound_ctrl:1
	v_max_u32_dpp v44, v44, v44 row_ror:2 row_mask:0xf bank_mask:0xf bound_ctrl:1
	v_max_u32_dpp v43, v43, v43 row_ror:4 row_mask:0xf bank_mask:0xf bound_ctrl:1
	v_max_u32_dpp v45, v45, v45 row_ror:2 row_mask:0xf bank_mask:0xf bound_ctrl:1
	v_max_u32_dpp v42, v42, v42 row_ror:4 row_mask:0xf bank_mask:0xf bound_ctrl:1
	v_max_u32_dpp v44, v44, v44 row_ror:4 row_mask:0xf bank_mask:0xf bound_ctrl:1
	v_max_u32_dpp v43, v43, v43 row_ror:8 row_mask:0xf bank_mask:0xf bound_ctrl:1
	v_max_u32_dpp v45, v45, v45 row_ror:4 row_mask:0xf bank_mask:0xf bound_ctrl:1
	v_max_u32_dpp v42, v42, v42 row_ror:8 row_mask:0xf bank_mask:0xf bound_ctrl:1
	v_max_u32_dpp v44, v44, v44 row_ror:8 row_mask:0xf bank_mask:0xf bound_ctrl:1
	v_cmp_eq_u32_e64 s[0:1], v12, v43
	v_max_u32_dpp v45, v45, v45 row_ror:8 row_mask:0xf bank_mask:0xf bound_ctrl:1
	v_cmp_eq_u32_e32 vcc, v4, v42
	v_cndmask_b32_e64 v12, v12, v14, s[0:1]
	v_cndmask_b32_e64 v14, v14, v15, s[0:1]
	v_cndmask_b32_e64 v15, v15, v22, s[0:1]
	v_cndmask_b32_e64 v22, v22, v23, s[0:1]
	v_cndmask_b32_e64 v23, v23, v24, s[0:1]
	v_cndmask_b32_e64 v24, v24, v25, s[0:1]
	v_cmp_eq_u32_e64 s[0:1], v26, v44
	v_cndmask_b32_e32 v4, v4, v6, vcc
	v_cndmask_b32_e32 v6, v6, v7, vcc
	v_cndmask_b32_e32 v7, v7, v8, vcc
	v_cndmask_b32_e32 v8, v8, v9, vcc
	v_cndmask_b32_e32 v9, v9, v10, vcc
	v_cndmask_b32_e32 v10, v10, v11, vcc
	v_cmp_eq_u32_e32 vcc, s40, v171
	v_cndmask_b32_e64 v26, v26, v28, s[0:1]
	v_cndmask_b32_e64 v28, v28, v29, s[0:1]
	v_cndmask_b32_e64 v29, v29, v30, s[0:1]
	v_cndmask_b32_e64 v30, v30, v31, s[0:1]
	v_cndmask_b32_e64 v31, v31, v32, s[0:1]
	v_cndmask_b32_e64 v32, v32, v33, s[0:1]
	v_cmp_eq_u32_e64 s[0:1], v34, v45
	s_add_i32 s40, s40, 1
	v_cndmask_b32_e32 v0, v0, v42, vcc
	v_cndmask_b32_e32 v1, v1, v43, vcc
	v_cndmask_b32_e32 v2, v2, v44, vcc
	v_cndmask_b32_e64 v34, v34, v36, s[0:1]
	v_cndmask_b32_e64 v36, v36, v37, s[0:1]
	v_cndmask_b32_e64 v37, v37, v38, s[0:1]
	v_cndmask_b32_e64 v38, v38, v39, s[0:1]
	v_cndmask_b32_e64 v39, v39, v40, s[0:1]
	v_cndmask_b32_e64 v40, v40, v41, s[0:1]
	v_cndmask_b32_e32 v3, v3, v45, vcc
	v_max_u32_dpp v43, v12, v12 row_ror:1 row_mask:0xf bank_mask:0xf bound_ctrl:1
	v_max_u32_dpp v42, v4, v4 row_ror:1 row_mask:0xf bank_mask:0xf bound_ctrl:1
	v_max_u32_dpp v44, v26, v26 row_ror:1 row_mask:0xf bank_mask:0xf bound_ctrl:1
	v_max_u32_dpp v43, v43, v43 row_ror:2 row_mask:0xf bank_mask:0xf bound_ctrl:1
	v_max_u32_dpp v45, v34, v34 row_ror:1 row_mask:0xf bank_mask:0xf bound_ctrl:1
	v_max_u32_dpp v42, v42, v42 row_ror:2 row_mask:0xf bank_mask:0xf bound_ctrl:1
	v_max_u32_dpp v44, v44, v44 row_ror:2 row_mask:0xf bank_mask:0xf bound_ctrl:1
	v_max_u32_dpp v43, v43, v43 row_ror:4 row_mask:0xf bank_mask:0xf bound_ctrl:1
	v_max_u32_dpp v45, v45, v45 row_ror:2 row_mask:0xf bank_mask:0xf bound_ctrl:1
	v_max_u32_dpp v42, v42, v42 row_ror:4 row_mask:0xf bank_mask:0xf bound_ctrl:1
	v_max_u32_dpp v44, v44, v44 row_ror:4 row_mask:0xf bank_mask:0xf bound_ctrl:1
	v_max_u32_dpp v43, v43, v43 row_ror:8 row_mask:0xf bank_mask:0xf bound_ctrl:1
	v_max_u32_dpp v45, v45, v45 row_ror:4 row_mask:0xf bank_mask:0xf bound_ctrl:1
	v_max_u32_dpp v42, v42, v42 row_ror:8 row_mask:0xf bank_mask:0xf bound_ctrl:1
	v_max_u32_dpp v44, v44, v44 row_ror:8 row_mask:0xf bank_mask:0xf bound_ctrl:1
	v_cmp_eq_u32_e64 s[0:1], v12, v43
	v_max_u32_dpp v45, v45, v45 row_ror:8 row_mask:0xf bank_mask:0xf bound_ctrl:1
	v_cmp_eq_u32_e32 vcc, v4, v42
	v_cndmask_b32_e64 v12, v12, v14, s[0:1]
	v_cndmask_b32_e64 v14, v14, v15, s[0:1]
	v_cndmask_b32_e64 v15, v15, v22, s[0:1]
	v_cndmask_b32_e64 v22, v22, v23, s[0:1]
	v_cndmask_b32_e64 v23, v23, v24, s[0:1]
	v_cmp_eq_u32_e64 s[0:1], v26, v44
	v_cndmask_b32_e32 v4, v4, v6, vcc
	v_cndmask_b32_e32 v6, v6, v7, vcc
	v_cndmask_b32_e32 v7, v7, v8, vcc
	v_cndmask_b32_e32 v8, v8, v9, vcc
	v_cndmask_b32_e32 v9, v9, v10, vcc
	v_cmp_eq_u32_e32 vcc, s40, v171
	v_cndmask_b32_e64 v26, v26, v28, s[0:1]
	v_cndmask_b32_e64 v28, v28, v29, s[0:1]
	v_cndmask_b32_e64 v29, v29, v30, s[0:1]
	v_cndmask_b32_e64 v30, v30, v31, s[0:1]
	v_cndmask_b32_e64 v31, v31, v32, s[0:1]
	v_cmp_eq_u32_e64 s[0:1], v34, v45
	s_add_i32 s40, s40, 1
	v_cndmask_b32_e32 v0, v0, v42, vcc
	v_cndmask_b32_e32 v1, v1, v43, vcc
	v_cndmask_b32_e32 v2, v2, v44, vcc
	v_cndmask_b32_e64 v34, v34, v36, s[0:1]
	v_cndmask_b32_e64 v36, v36, v37, s[0:1]
	v_cndmask_b32_e64 v37, v37, v38, s[0:1]
	v_cndmask_b32_e64 v38, v38, v39, s[0:1]
	v_cndmask_b32_e64 v39, v39, v40, s[0:1]
	v_cndmask_b32_e32 v3, v3, v45, vcc
	v_max_u32_dpp v43, v12, v12 row_ror:1 row_mask:0xf bank_mask:0xf bound_ctrl:1
	v_max_u32_dpp v42, v4, v4 row_ror:1 row_mask:0xf bank_mask:0xf bound_ctrl:1
	v_max_u32_dpp v44, v26, v26 row_ror:1 row_mask:0xf bank_mask:0xf bound_ctrl:1
	v_max_u32_dpp v43, v43, v43 row_ror:2 row_mask:0xf bank_mask:0xf bound_ctrl:1
	v_max_u32_dpp v45, v34, v34 row_ror:1 row_mask:0xf bank_mask:0xf bound_ctrl:1
	v_max_u32_dpp v42, v42, v42 row_ror:2 row_mask:0xf bank_mask:0xf bound_ctrl:1
	v_max_u32_dpp v44, v44, v44 row_ror:2 row_mask:0xf bank_mask:0xf bound_ctrl:1
	v_max_u32_dpp v43, v43, v43 row_ror:4 row_mask:0xf bank_mask:0xf bound_ctrl:1
	v_max_u32_dpp v45, v45, v45 row_ror:2 row_mask:0xf bank_mask:0xf bound_ctrl:1
	v_max_u32_dpp v42, v42, v42 row_ror:4 row_mask:0xf bank_mask:0xf bound_ctrl:1
	v_max_u32_dpp v44, v44, v44 row_ror:4 row_mask:0xf bank_mask:0xf bound_ctrl:1
	v_max_u32_dpp v43, v43, v43 row_ror:8 row_mask:0xf bank_mask:0xf bound_ctrl:1
	v_max_u32_dpp v45, v45, v45 row_ror:4 row_mask:0xf bank_mask:0xf bound_ctrl:1
	v_max_u32_dpp v42, v42, v42 row_ror:8 row_mask:0xf bank_mask:0xf bound_ctrl:1
	v_max_u32_dpp v44, v44, v44 row_ror:8 row_mask:0xf bank_mask:0xf bound_ctrl:1
	v_cmp_eq_u32_e64 s[0:1], v12, v43
	v_max_u32_dpp v45, v45, v45 row_ror:8 row_mask:0xf bank_mask:0xf bound_ctrl:1
	v_cmp_eq_u32_e32 vcc, v4, v42
	v_cndmask_b32_e64 v12, v12, v14, s[0:1]
	v_cndmask_b32_e64 v14, v14, v15, s[0:1]
	v_cndmask_b32_e64 v15, v15, v22, s[0:1]
	v_cndmask_b32_e64 v22, v22, v23, s[0:1]
	v_cmp_eq_u32_e64 s[0:1], v26, v44
	v_cndmask_b32_e32 v4, v4, v6, vcc
	v_cndmask_b32_e32 v6, v6, v7, vcc
	v_cndmask_b32_e32 v7, v7, v8, vcc
	v_cndmask_b32_e32 v8, v8, v9, vcc
	v_cmp_eq_u32_e32 vcc, s40, v171
	v_cndmask_b32_e64 v26, v26, v28, s[0:1]
	v_cndmask_b32_e64 v28, v28, v29, s[0:1]
	v_cndmask_b32_e64 v29, v29, v30, s[0:1]
	v_cndmask_b32_e64 v30, v30, v31, s[0:1]
	v_cmp_eq_u32_e64 s[0:1], v34, v45
	s_add_i32 s40, s40, 1
	v_cndmask_b32_e32 v0, v0, v42, vcc
	v_cndmask_b32_e32 v1, v1, v43, vcc
	v_cndmask_b32_e32 v2, v2, v44, vcc
	v_cndmask_b32_e64 v34, v34, v36, s[0:1]
	v_cndmask_b32_e64 v36, v36, v37, s[0:1]
	v_cndmask_b32_e64 v37, v37, v38, s[0:1]
	v_cndmask_b32_e64 v38, v38, v39, s[0:1]
	v_cndmask_b32_e32 v3, v3, v45, vcc
	v_max_u32_dpp v43, v12, v12 row_ror:1 row_mask:0xf bank_mask:0xf bound_ctrl:1
	v_max_u32_dpp v42, v4, v4 row_ror:1 row_mask:0xf bank_mask:0xf bound_ctrl:1
	v_max_u32_dpp v44, v26, v26 row_ror:1 row_mask:0xf bank_mask:0xf bound_ctrl:1
	v_max_u32_dpp v43, v43, v43 row_ror:2 row_mask:0xf bank_mask:0xf bound_ctrl:1
	v_max_u32_dpp v45, v34, v34 row_ror:1 row_mask:0xf bank_mask:0xf bound_ctrl:1
	v_max_u32_dpp v42, v42, v42 row_ror:2 row_mask:0xf bank_mask:0xf bound_ctrl:1
	v_max_u32_dpp v44, v44, v44 row_ror:2 row_mask:0xf bank_mask:0xf bound_ctrl:1
	v_max_u32_dpp v43, v43, v43 row_ror:4 row_mask:0xf bank_mask:0xf bound_ctrl:1
	v_max_u32_dpp v45, v45, v45 row_ror:2 row_mask:0xf bank_mask:0xf bound_ctrl:1
	v_max_u32_dpp v42, v42, v42 row_ror:4 row_mask:0xf bank_mask:0xf bound_ctrl:1
	v_max_u32_dpp v44, v44, v44 row_ror:4 row_mask:0xf bank_mask:0xf bound_ctrl:1
	v_max_u32_dpp v43, v43, v43 row_ror:8 row_mask:0xf bank_mask:0xf bound_ctrl:1
	v_max_u32_dpp v45, v45, v45 row_ror:4 row_mask:0xf bank_mask:0xf bound_ctrl:1
	v_max_u32_dpp v42, v42, v42 row_ror:8 row_mask:0xf bank_mask:0xf bound_ctrl:1
	v_max_u32_dpp v44, v44, v44 row_ror:8 row_mask:0xf bank_mask:0xf bound_ctrl:1
	v_cmp_eq_u32_e64 s[0:1], v12, v43
	v_max_u32_dpp v45, v45, v45 row_ror:8 row_mask:0xf bank_mask:0xf bound_ctrl:1
	v_cmp_eq_u32_e32 vcc, v4, v42
	v_cndmask_b32_e64 v12, v12, v14, s[0:1]
	v_cndmask_b32_e64 v14, v14, v15, s[0:1]
	v_cndmask_b32_e64 v15, v15, v22, s[0:1]
	v_cmp_eq_u32_e64 s[0:1], v26, v44
	v_cndmask_b32_e32 v4, v4, v6, vcc
	v_cndmask_b32_e32 v6, v6, v7, vcc
	v_cndmask_b32_e32 v7, v7, v8, vcc
	v_cmp_eq_u32_e32 vcc, s40, v171
	v_cndmask_b32_e64 v26, v26, v28, s[0:1]
	v_cndmask_b32_e64 v28, v28, v29, s[0:1]
	v_cndmask_b32_e64 v29, v29, v30, s[0:1]
	v_cmp_eq_u32_e64 s[0:1], v34, v45
	s_add_i32 s40, s40, 1
	v_cndmask_b32_e32 v0, v0, v42, vcc
	v_cndmask_b32_e32 v1, v1, v43, vcc
	v_cndmask_b32_e32 v2, v2, v44, vcc
	v_cndmask_b32_e64 v34, v34, v36, s[0:1]
	v_cndmask_b32_e64 v36, v36, v37, s[0:1]
	v_cndmask_b32_e64 v37, v37, v38, s[0:1]
	v_cndmask_b32_e32 v3, v3, v45, vcc
	v_max_u32_dpp v43, v12, v12 row_ror:1 row_mask:0xf bank_mask:0xf bound_ctrl:1
	v_max_u32_dpp v42, v4, v4 row_ror:1 row_mask:0xf bank_mask:0xf bound_ctrl:1
	v_max_u32_dpp v44, v26, v26 row_ror:1 row_mask:0xf bank_mask:0xf bound_ctrl:1
	v_max_u32_dpp v43, v43, v43 row_ror:2 row_mask:0xf bank_mask:0xf bound_ctrl:1
	v_max_u32_dpp v45, v34, v34 row_ror:1 row_mask:0xf bank_mask:0xf bound_ctrl:1
	v_max_u32_dpp v42, v42, v42 row_ror:2 row_mask:0xf bank_mask:0xf bound_ctrl:1
	v_max_u32_dpp v44, v44, v44 row_ror:2 row_mask:0xf bank_mask:0xf bound_ctrl:1
	v_max_u32_dpp v43, v43, v43 row_ror:4 row_mask:0xf bank_mask:0xf bound_ctrl:1
	v_max_u32_dpp v45, v45, v45 row_ror:2 row_mask:0xf bank_mask:0xf bound_ctrl:1
	v_max_u32_dpp v42, v42, v42 row_ror:4 row_mask:0xf bank_mask:0xf bound_ctrl:1
	v_max_u32_dpp v44, v44, v44 row_ror:4 row_mask:0xf bank_mask:0xf bound_ctrl:1
	v_max_u32_dpp v43, v43, v43 row_ror:8 row_mask:0xf bank_mask:0xf bound_ctrl:1
	v_max_u32_dpp v45, v45, v45 row_ror:4 row_mask:0xf bank_mask:0xf bound_ctrl:1
	v_max_u32_dpp v42, v42, v42 row_ror:8 row_mask:0xf bank_mask:0xf bound_ctrl:1
	v_max_u32_dpp v44, v44, v44 row_ror:8 row_mask:0xf bank_mask:0xf bound_ctrl:1
	v_cmp_eq_u32_e64 s[0:1], v12, v43
	v_max_u32_dpp v45, v45, v45 row_ror:8 row_mask:0xf bank_mask:0xf bound_ctrl:1
	v_cmp_eq_u32_e32 vcc, v4, v42
	v_cndmask_b32_e64 v12, v12, v14, s[0:1]
	v_cndmask_b32_e64 v14, v14, v15, s[0:1]
	v_cmp_eq_u32_e64 s[0:1], v26, v44
	v_cndmask_b32_e32 v4, v4, v6, vcc
	v_cndmask_b32_e32 v6, v6, v7, vcc
	v_cmp_eq_u32_e32 vcc, s40, v171
	v_cndmask_b32_e64 v26, v26, v28, s[0:1]
	v_cndmask_b32_e64 v28, v28, v29, s[0:1]
	v_cmp_eq_u32_e64 s[0:1], v34, v45
	s_add_i32 s40, s40, 1
	v_cndmask_b32_e32 v0, v0, v42, vcc
	v_cndmask_b32_e32 v1, v1, v43, vcc
	v_cndmask_b32_e32 v2, v2, v44, vcc
	v_cndmask_b32_e64 v34, v34, v36, s[0:1]
	v_cndmask_b32_e64 v36, v36, v37, s[0:1]
	v_cndmask_b32_e32 v3, v3, v45, vcc
	v_max_u32_dpp v43, v12, v12 row_ror:1 row_mask:0xf bank_mask:0xf bound_ctrl:1
	v_max_u32_dpp v42, v4, v4 row_ror:1 row_mask:0xf bank_mask:0xf bound_ctrl:1
	v_max_u32_dpp v44, v26, v26 row_ror:1 row_mask:0xf bank_mask:0xf bound_ctrl:1
	v_max_u32_dpp v43, v43, v43 row_ror:2 row_mask:0xf bank_mask:0xf bound_ctrl:1
	v_max_u32_dpp v45, v34, v34 row_ror:1 row_mask:0xf bank_mask:0xf bound_ctrl:1
	v_max_u32_dpp v42, v42, v42 row_ror:2 row_mask:0xf bank_mask:0xf bound_ctrl:1
	v_max_u32_dpp v44, v44, v44 row_ror:2 row_mask:0xf bank_mask:0xf bound_ctrl:1
	v_max_u32_dpp v43, v43, v43 row_ror:4 row_mask:0xf bank_mask:0xf bound_ctrl:1
	v_max_u32_dpp v45, v45, v45 row_ror:2 row_mask:0xf bank_mask:0xf bound_ctrl:1
	v_max_u32_dpp v42, v42, v42 row_ror:4 row_mask:0xf bank_mask:0xf bound_ctrl:1
	v_max_u32_dpp v44, v44, v44 row_ror:4 row_mask:0xf bank_mask:0xf bound_ctrl:1
	v_max_u32_dpp v43, v43, v43 row_ror:8 row_mask:0xf bank_mask:0xf bound_ctrl:1
	v_max_u32_dpp v45, v45, v45 row_ror:4 row_mask:0xf bank_mask:0xf bound_ctrl:1
	v_max_u32_dpp v42, v42, v42 row_ror:8 row_mask:0xf bank_mask:0xf bound_ctrl:1
	v_max_u32_dpp v44, v44, v44 row_ror:8 row_mask:0xf bank_mask:0xf bound_ctrl:1
	v_cmp_eq_u32_e64 s[0:1], v12, v43
	v_max_u32_dpp v45, v45, v45 row_ror:8 row_mask:0xf bank_mask:0xf bound_ctrl:1
	v_cmp_eq_u32_e32 vcc, v4, v42
	v_cndmask_b32_e64 v12, v12, v14, s[0:1]
	v_cmp_eq_u32_e64 s[0:1], v26, v44
	v_cndmask_b32_e32 v4, v4, v6, vcc
	v_cmp_eq_u32_e32 vcc, s40, v171
	v_cndmask_b32_e64 v26, v26, v28, s[0:1]
	v_cmp_eq_u32_e64 s[0:1], v34, v45
	s_add_i32 s40, s40, 1
	v_cndmask_b32_e32 v0, v0, v42, vcc
	v_cndmask_b32_e32 v1, v1, v43, vcc
	v_cndmask_b32_e32 v2, v2, v44, vcc
	v_cndmask_b32_e64 v34, v34, v36, s[0:1]
	v_cndmask_b32_e32 v3, v3, v45, vcc
	v_max_u32_dpp v43, v12, v12 row_ror:1 row_mask:0xf bank_mask:0xf bound_ctrl:1
	v_max_u32_dpp v42, v4, v4 row_ror:1 row_mask:0xf bank_mask:0xf bound_ctrl:1
	v_max_u32_dpp v44, v26, v26 row_ror:1 row_mask:0xf bank_mask:0xf bound_ctrl:1
	v_max_u32_dpp v43, v43, v43 row_ror:2 row_mask:0xf bank_mask:0xf bound_ctrl:1
	v_max_u32_dpp v45, v34, v34 row_ror:1 row_mask:0xf bank_mask:0xf bound_ctrl:1
	v_max_u32_dpp v42, v42, v42 row_ror:2 row_mask:0xf bank_mask:0xf bound_ctrl:1
	v_max_u32_dpp v44, v44, v44 row_ror:2 row_mask:0xf bank_mask:0xf bound_ctrl:1
	v_max_u32_dpp v43, v43, v43 row_ror:4 row_mask:0xf bank_mask:0xf bound_ctrl:1
	v_max_u32_dpp v45, v45, v45 row_ror:2 row_mask:0xf bank_mask:0xf bound_ctrl:1
	v_max_u32_dpp v42, v42, v42 row_ror:4 row_mask:0xf bank_mask:0xf bound_ctrl:1
	v_max_u32_dpp v44, v44, v44 row_ror:4 row_mask:0xf bank_mask:0xf bound_ctrl:1
	v_max_u32_dpp v43, v43, v43 row_ror:8 row_mask:0xf bank_mask:0xf bound_ctrl:1
	v_max_u32_dpp v45, v45, v45 row_ror:4 row_mask:0xf bank_mask:0xf bound_ctrl:1
	v_max_u32_dpp v42, v42, v42 row_ror:8 row_mask:0xf bank_mask:0xf bound_ctrl:1
	v_max_u32_dpp v44, v44, v44 row_ror:8 row_mask:0xf bank_mask:0xf bound_ctrl:1
	v_max_u32_dpp v45, v45, v45 row_ror:8 row_mask:0xf bank_mask:0xf bound_ctrl:1
	v_cmp_eq_u32_e32 vcc, s40, v171
	s_add_i32 s40, s40, 1
	s_nop 0
	v_cndmask_b32_e32 v0, v0, v42, vcc
	v_cndmask_b32_e32 v1, v1, v43, vcc
	v_cndmask_b32_e32 v2, v2, v44, vcc
	v_cndmask_b32_e32 v3, v3, v45, vcc
	v_cmp_lt_i32_e32 vcc, -1, v18
	v_mov_b32_e32 v6, 0
	v_mov_b32_e32 v7, 0
	v_cndmask_b32_e64 v4, v217, -1, vcc
	v_cmp_lt_i32_e32 vcc, -1, v0
	v_bitop3_b32 v8, v4, v18, s67 bitop3:0x78
	ds_bpermute_b32 v10, v198, v8
	v_cndmask_b32_e64 v4, v217, -1, vcc
	v_bitop3_b32 v9, v4, v0, s67 bitop3:0x78
	ds_bpermute_b32 v4, v196, v8
	ds_bpermute_b32 v5, v197, v9
	ds_bpermute_b32 v11, v199, v9
	s_and_saveexec_b64 s[0:1], s[6:7]
	s_cbranch_execz .LBB0_1352
	s_waitcnt lgkmcnt(0)
	v_add_f32_e32 v7, v10, v11
	v_cmp_lt_i32_e32 vcc, -1, v7
	s_nop 1
	v_cndmask_b32_e32 v10, -1, v217, vcc
	v_bitop3_b32 v7, v10, s59, v7 bitop3:0x48
	v_bitop3_b32 v7, v7, s54, v172 bitop3:0x36
